# dense attention item loop shifted +24 bytes (loop-head offset 20 mod 64), complementary pad after the phase
# baseline (speedup 1.0000x reference)
; DI int fresh_lane() { int l; asm volatile("v_mbcnt_lo_u32_b32 %0, -1, 0\n\tv_mbcnt_hi_u32_b32 %0, -1, %0" : "=v"(l)); return l; }
; #define FRESH_IDS() int tid_ = wave_s * 64 + fresh_lane(); asm volatile("" : "+v"(tid_)); const int tid = tid_, lane = tid & 63, wave = wave_s; (void)tid; (void)lane; (void)wave
; __global__ void __launch_bounds__(512, 2) fwd_kernel(Params p) {
;     ...
;     for (int rep_ = 0; rep_ < REP_ATTNC; ++rep_) { FRESH_IDS();
;         const int G_ = (int)gridDim.x, vcu = (G_ % 8 == 0) ? ((int)blockIdx.x & 7) * (G_ >> 3) + ((int)blockIdx.x >> 3) : (int)blockIdx.x;
;         for (int item = vcu; item < 1024; item += G_) {
;             const int qb = item & 15, head = (item >> 4) & 7, b = item >> 7, kvh = head >> 2;
;             int tl = wave * 64 + fresh_lane(); asm volatile("" : "+v"(tl));
;             const size_t qrow = (size_t)NCTX + (size_t)b * SEQ + qb * 256;
;             __syncthreads();
.LBB0_1525:
	s_or_b64 exec, exec, s[0:1]
	s_and_b32 s1, s75, 7
	s_ashr_i32 s2, s30, 3
	s_mul_i32 s1, s2, s1
	s_ashr_i32 s2, s75, 3
	s_and_b32 s0, s30, 7
	s_add_i32 s1, s1, s2
	s_cmp_eq_u32 s0, 0
	s_waitcnt lgkmcnt(0)
	s_barrier
	v_mbcnt_lo_u32_b32 v0, -1, 0
	v_mbcnt_hi_u32_b32 v0, -1, v0
	s_cselect_b32 s2, s1, s75
	s_mov_b32 s56, 0
	v_add_u32_e32 v0, s74, v0
	s_cmpk_gt_i32 s2, 0x3ff
	s_cbranch_scc1 .LBB0_1547
	s_add_u32 s3, s28, 0x1e500000
	s_addc_u32 s11, s29, 0
	s_add_u32 s0, s28, 0x1e512000
	s_addc_u32 s1, s29, 0
	v_mov_b32_e32 v177, 0
	s_mov_b32 s14, 0x42b504f3
	s_mov_b32 s10, 0x3e0293ee
	v_mov_b32_e32 v180, 0xf149f2ca
	s_mov_b64 s[12:13], 0x8000
	v_mov_b32_e32 v181, 0x110000
	s_nop 0
	s_nop 0
	s_nop 0
	s_nop 0
	s_nop 0
	s_nop 0
	s_branch .LBB0_1528

; DI void xcd_barrier(const XcdBarrier& b, int tid) {
;     asm volatile("s_waitcnt vmcnt(0)" ::: "memory");
;     __syncthreads();
;     if (tid == 0) {
;         unsigned* bar = b.bar;
;         __builtin_amdgcn_s_waitcnt(0);
;         unsigned nloc = b.st[0], nx = b.st[1];
;         if (nloc == 0u) { xcd_barrier_complete(bar, b.x, nloc, nx); b.st[0] = nloc; b.st[1] = nx; }
.LBB0_1547:
	s_nop 0
	s_nop 0
	s_nop 0
	s_nop 0
	s_nop 0
	s_nop 0
	s_nop 0
	s_nop 0
	s_nop 0
	s_nop 0
	v_mbcnt_lo_u32_b32 v0, -1, 0
	v_mbcnt_hi_u32_b32 v0, -1, v0
	s_nop 0
	v_add_u32_e32 v0, s74, v0
	s_waitcnt vmcnt(0)
	s_waitcnt vmcnt(63) expcnt(7) lgkmcnt(15)
	v_cmp_eq_u32_e32 vcc, 0, v0
	s_barrier
	s_and_saveexec_b64 s[0:1], vcc
	v_readlane_b32 s59, v254, 12
	s_cbranch_execz .LBB0_1599
	s_add_i32 s2, 0, 0x23ff0
	v_mov_b32_e32 v0, s2
	s_waitcnt vmcnt(0) expcnt(0) lgkmcnt(0)
	ds_read_b32 v2, v0
	s_add_i32 s2, 0, 0x23ff4
	v_mov_b32_e32 v0, s2
	ds_read_b32 v0, v0
	s_waitcnt lgkmcnt(1)
	v_cmp_ne_u32_e32 vcc, 0, v2
	s_cbranch_vccnz .LBB0_1563
	s_mov_b32 s2, 1
	v_mov_b32_e32 v16, 0
	s_branch .LBB0_1551
